# attention: next-tile LDS-DMA issue interleaved into the QK MFMA block (saddr+voffset form, no VGPR temps)
# speedup vs baseline: 1.0097x; 1.0097x over previous
.LBB0_999:
	s_add_i32 s28, s29, 1
	s_cmp_lt_u32 s29, 3
	s_cselect_b32 s8, s27, s13
	s_ashr_i32 s9, s8, 31
	s_mul_i32 s10, s8, 0xc00
	s_mul_hi_i32 s11, s8, 0xc00
	s_add_u32 s10, s16, s10
	s_addc_u32 s11, s17, s11
	s_lshl_b64 s[8:9], s[8:9], 1
	s_add_u32 vcc_lo, s18, s8
	s_addc_u32 vcc_hi, s19, s9
	s_bitcmp1_b32 s28, 0
	s_cselect_b32 s12, 0xa800, 0
	v_readfirstlane_b32 s30, v181
	s_add_i32 s30, s30, s12
	s_bitcmp1_b32 s29, 0
	s_cselect_b32 s8, 0xa800, 0
	v_add_u32_e32 v116, s8, v198
	ds_read_b128 v[116:119], v116
	v_add_u32_e32 v124, s8, v199
	ds_read_b128 v[124:127], v124
	v_add_u32_e32 v128, s8, v200
	ds_read_b128 v[128:131], v128
	v_add_u32_e32 v136, s8, v201
	ds_read_b128 v[136:139], v136
	v_add_u32_e32 v132, s8, v225
	ds_read_b128 v[132:135], v132
	v_add_u32_e32 v140, s8, v226
	ds_read_b128 v[140:143], v140
	s_waitcnt lgkmcnt(5)
	v_mfma_f32_16x16x32_bf16 v[112:115], v[116:119], v[104:107], 0
	v_mfma_f32_16x16x32_bf16 v[120:123], v[116:119], v[108:111], 0
	v_add_u32_e32 v204, s8, v234
	ds_read_b128 v[204:207], v204
	s_waitcnt lgkmcnt(5)
	v_mfma_f32_16x16x32_bf16 v[112:115], v[124:127], v[96:99], v[112:115]
	v_mfma_f32_16x16x32_bf16 v[120:123], v[124:127], v[100:103], v[120:123]
	v_add_u32_e32 v208, s8, v235
	ds_read_b128 v[208:211], v208
	s_add_i32 m0, s30, 0x0
	s_waitcnt lgkmcnt(5)
	v_mfma_f32_16x16x32_bf16 v[112:115], v[128:131], v[88:91], v[112:115]
	v_mfma_f32_16x16x32_bf16 v[120:123], v[128:131], v[92:95], v[120:123]
	global_load_lds_dwordx4 v158, s[10:11]
	v_add_u32_e32 v128, s8, v236
	ds_read_b128 v[128:131], v128
	s_waitcnt lgkmcnt(5)
	v_mfma_f32_16x16x32_bf16 v[112:115], v[136:139], v[80:83], v[112:115]
	v_mfma_f32_16x16x32_bf16 v[120:123], v[136:139], v[84:87], v[120:123]
	v_add_u32_e32 v136, s8, v237
	ds_read_b128 v[136:139], v136
	s_waitcnt lgkmcnt(5)
	v_mfma_f32_16x16x32_bf16 v[112:115], v[132:135], v[72:75], v[112:115]
	v_mfma_f32_16x16x32_bf16 v[120:123], v[132:135], v[76:79], v[120:123]
	v_add_u32_e32 v132, s8, v238
	ds_read_b128 v[132:135], v132
	s_add_i32 m0, s30, 0x2000
	s_waitcnt lgkmcnt(5)
	v_mfma_f32_16x16x32_bf16 v[112:115], v[140:143], v[64:67], v[112:115]
	v_mfma_f32_16x16x32_bf16 v[120:123], v[140:143], v[68:71], v[120:123]
	global_load_lds_dwordx4 v172, s[10:11]
	v_add_u32_e32 v140, s8, v239
	ds_read_b128 v[140:143], v140
	s_waitcnt lgkmcnt(5)
	v_mfma_f32_16x16x32_bf16 v[116:119], v[204:207], v[104:107], 0
	v_mfma_f32_16x16x32_bf16 v[124:127], v[204:207], v[108:111], 0
	v_add_u32_e32 v204, s8, v240
	ds_read_b128 v[204:207], v204
	s_waitcnt lgkmcnt(5)
	v_mfma_f32_16x16x32_bf16 v[116:119], v[208:211], v[96:99], v[116:119]
	v_mfma_f32_16x16x32_bf16 v[124:127], v[208:211], v[100:103], v[124:127]
	v_add_u32_e32 v208, s8, v241
	ds_read_b128 v[208:211], v208
	s_add_i32 m0, s30, 0x4000
	s_waitcnt lgkmcnt(5)
	v_mfma_f32_16x16x32_bf16 v[116:119], v[128:131], v[88:91], v[116:119]
	v_mfma_f32_16x16x32_bf16 v[124:127], v[128:131], v[92:95], v[124:127]
	global_load_lds_dwordx4 v174, s[10:11]
	s_waitcnt lgkmcnt(4)
	v_mfma_f32_16x16x32_bf16 v[116:119], v[136:139], v[80:83], v[116:119]
	v_mfma_f32_16x16x32_bf16 v[124:127], v[136:139], v[84:87], v[124:127]
	s_waitcnt lgkmcnt(3)
	v_mfma_f32_16x16x32_bf16 v[116:119], v[132:135], v[72:75], v[116:119]
	v_mfma_f32_16x16x32_bf16 v[124:127], v[132:135], v[76:79], v[124:127]
	v_add_u32_e32 v132, s8, v242
	ds_read_b128 v[132:135], v132
	s_add_i32 m0, s30, 0x6000
	s_waitcnt lgkmcnt(3)
	v_mfma_f32_16x16x32_bf16 v[116:119], v[140:143], v[64:67], v[116:119]
	v_mfma_f32_16x16x32_bf16 v[124:127], v[140:143], v[68:71], v[124:127]
	global_load_lds_dwordx4 v176, vcc
	v_add_u32_e32 v140, s8, v243
	ds_read_b128 v[140:143], v140
	s_waitcnt lgkmcnt(3)
	v_mfma_f32_16x16x32_bf16 v[136:139], v[204:207], v[104:107], 0
	v_mfma_f32_16x16x32_bf16 v[128:131], v[204:207], v[108:111], 0
	v_add_u32_e32 v204, s8, v244
	ds_read_b128 v[204:207], v204
	s_waitcnt lgkmcnt(3)
	v_mfma_f32_16x16x32_bf16 v[136:139], v[208:211], v[96:99], v[136:139]
	v_mfma_f32_16x16x32_bf16 v[128:131], v[208:211], v[100:103], v[128:131]
	v_add_u32_e32 v208, s8, v245
	ds_read_b128 v[208:211], v208
	s_add_i32 m0, s30, 0x8000
	s_waitcnt lgkmcnt(3)
	v_mfma_f32_16x16x32_bf16 v[136:139], v[132:135], v[88:91], v[136:139]
	v_mfma_f32_16x16x32_bf16 v[128:131], v[132:135], v[92:95], v[128:131]
	global_load_lds_dwordx4 v178, vcc
	s_waitcnt lgkmcnt(2)
	v_mfma_f32_16x16x32_bf16 v[136:139], v[140:143], v[80:83], v[136:139]
	v_mfma_f32_16x16x32_bf16 v[128:131], v[140:143], v[84:87], v[128:131]
	s_waitcnt lgkmcnt(1)
	v_mfma_f32_16x16x32_bf16 v[136:139], v[204:207], v[72:75], v[136:139]
	v_mfma_f32_16x16x32_bf16 v[128:131], v[204:207], v[76:79], v[128:131]
	v_add_u32_e32 v204, s8, v246
	ds_read_b128 v[204:207], v204
	s_waitcnt lgkmcnt(1)
	v_mfma_f32_16x16x32_bf16 v[136:139], v[208:211], v[64:67], v[136:139]
	v_mfma_f32_16x16x32_bf16 v[128:131], v[208:211], v[68:71], v[128:131]
	s_cmp_lg_u64 s[6:7], 0
	s_cbranch_scc0 .Lat_v2skip
	s_add_i32 m0, s30, 0xa000
	s_nop 0
	global_load_lds_dwordx4 v160, vcc
.Lat_v2skip:
	v_add_u32_e32 v208, s8, v247
	ds_read_b128 v[208:211], v208
	s_waitcnt lgkmcnt(1)
	v_mfma_f32_16x16x32_bf16 v[140:143], v[204:207], v[104:107], 0
	v_mfma_f32_16x16x32_bf16 v[132:135], v[204:207], v[108:111], 0
	v_add_u32_e32 v204, s8, v248
	ds_read_b128 v[204:207], v204
	s_waitcnt lgkmcnt(1)
	v_mfma_f32_16x16x32_bf16 v[140:143], v[208:211], v[96:99], v[140:143]
	v_mfma_f32_16x16x32_bf16 v[132:135], v[208:211], v[100:103], v[132:135]
	v_add_u32_e32 v208, s8, v249
	ds_read_b128 v[208:211], v208
	s_waitcnt lgkmcnt(1)
	v_mfma_f32_16x16x32_bf16 v[140:143], v[204:207], v[88:91], v[140:143]
	v_mfma_f32_16x16x32_bf16 v[132:135], v[204:207], v[92:95], v[132:135]
	v_add_u32_e32 v204, s8, v250
	ds_read_b128 v[204:207], v204
	s_waitcnt lgkmcnt(1)
	v_mfma_f32_16x16x32_bf16 v[140:143], v[208:211], v[80:83], v[140:143]
	v_mfma_f32_16x16x32_bf16 v[132:135], v[208:211], v[84:87], v[132:135]
	v_add_u32_e32 v208, s8, v251
	ds_read_b128 v[208:211], v208
	s_waitcnt lgkmcnt(1)
	v_mfma_f32_16x16x32_bf16 v[140:143], v[204:207], v[72:75], v[140:143]
	v_mfma_f32_16x16x32_bf16 v[132:135], v[204:207], v[76:79], v[132:135]
	s_waitcnt lgkmcnt(0)
	v_mfma_f32_16x16x32_bf16 v[140:143], v[208:211], v[64:67], v[140:143]
	v_mfma_f32_16x16x32_bf16 v[132:135], v[208:211], v[68:71], v[132:135]
	s_nop 7
	v_fmamk_f32 v112, v112, 0x3dd53b94, v157
	v_fmamk_f32 v113, v113, 0x3dd53b94, v157
	v_fmamk_f32 v114, v114, 0x3dd53b94, v157
	v_exp_f32_e32 v112, v112
	v_fmamk_f32 v115, v115, 0x3dd53b94, v157
	v_exp_f32_e32 v113, v113
	v_fmamk_f32 v116, v116, 0x3dd53b94, v157
	v_exp_f32_e32 v114, v114
	v_fmamk_f32 v117, v117, 0x3dd53b94, v157
	v_exp_f32_e32 v115, v115
	v_fmamk_f32 v118, v118, 0x3dd53b94, v157
	v_exp_f32_e32 v116, v116
	v_fmamk_f32 v119, v119, 0x3dd53b94, v157
	v_exp_f32_e32 v117, v117
	v_fmamk_f32 v136, v136, 0x3dd53b94, v157
	v_exp_f32_e32 v118, v118
	v_fmamk_f32 v137, v137, 0x3dd53b94, v157
	v_exp_f32_e32 v119, v119
	v_fmamk_f32 v138, v138, 0x3dd53b94, v157
	v_exp_f32_e32 v136, v136
	v_fmamk_f32 v139, v139, 0x3dd53b94, v157
	v_exp_f32_e32 v137, v137
	v_fmamk_f32 v140, v140, 0x3dd53b94, v157
	v_exp_f32_e32 v138, v138
	v_fmamk_f32 v141, v141, 0x3dd53b94, v157
	v_exp_f32_e32 v139, v139
	v_fmamk_f32 v142, v142, 0x3dd53b94, v157
	v_exp_f32_e32 v140, v140
	v_fmamk_f32 v143, v143, 0x3dd53b94, v157
	v_exp_f32_e32 v141, v141
	v_exp_f32_e32 v142, v142
	v_exp_f32_e32 v143, v143
	s_nop 0
	v_add_f32_e32 v204, v112, v113
	v_add_f32_e32 v205, v114, v115
	v_add_f32_e32 v206, v116, v117
	v_add_f32_e32 v207, v118, v119
	v_add_f32_e32 v208, v136, v137
	v_add_f32_e32 v209, v138, v139
	v_add_f32_e32 v210, v140, v141
	v_add_f32_e32 v211, v142, v143
	v_add_f32_e32 v204, v204, v205
	v_add_f32_e32 v206, v206, v207
	v_add_f32_e32 v208, v208, v209
	v_add_f32_e32 v210, v210, v211
	v_add_f32_e32 v204, v204, v206
	v_add_f32_e32 v208, v208, v210
	v_add_f32_e32 v195, v204, v208
	v_fmamk_f32 v120, v120, 0x3dd53b94, v155
	v_fmamk_f32 v121, v121, 0x3dd53b94, v155
	v_fmamk_f32 v122, v122, 0x3dd53b94, v155
	v_exp_f32_e32 v120, v120
	v_fmamk_f32 v123, v123, 0x3dd53b94, v155
	v_exp_f32_e32 v121, v121
	v_fmamk_f32 v124, v124, 0x3dd53b94, v155
	v_exp_f32_e32 v122, v122
	v_fmamk_f32 v125, v125, 0x3dd53b94, v155
	v_exp_f32_e32 v123, v123
	v_fmamk_f32 v126, v126, 0x3dd53b94, v155
	v_exp_f32_e32 v124, v124
	v_fmamk_f32 v127, v127, 0x3dd53b94, v155
	v_exp_f32_e32 v125, v125
	v_fmamk_f32 v128, v128, 0x3dd53b94, v155
	v_exp_f32_e32 v126, v126
	v_fmamk_f32 v129, v129, 0x3dd53b94, v155
	v_exp_f32_e32 v127, v127
	v_fmamk_f32 v130, v130, 0x3dd53b94, v155
	v_exp_f32_e32 v128, v128
	v_fmamk_f32 v131, v131, 0x3dd53b94, v155
	v_exp_f32_e32 v129, v129
	v_fmamk_f32 v132, v132, 0x3dd53b94, v155
	v_exp_f32_e32 v130, v130
	v_fmamk_f32 v133, v133, 0x3dd53b94, v155
	v_exp_f32_e32 v131, v131
	v_fmamk_f32 v134, v134, 0x3dd53b94, v155
	v_exp_f32_e32 v132, v132
	v_fmamk_f32 v135, v135, 0x3dd53b94, v155
	v_exp_f32_e32 v133, v133
	v_exp_f32_e32 v134, v134
	v_exp_f32_e32 v135, v135
	s_nop 0
	v_add_f32_e32 v204, v120, v121
	v_add_f32_e32 v205, v122, v123
	v_add_f32_e32 v206, v124, v125
	v_add_f32_e32 v207, v126, v127
	v_add_f32_e32 v208, v128, v129
	v_add_f32_e32 v209, v130, v131
	v_add_f32_e32 v210, v132, v133
	v_add_f32_e32 v211, v134, v135
	v_add_f32_e32 v204, v204, v205
	v_add_f32_e32 v206, v206, v207
	v_add_f32_e32 v208, v208, v209
	v_add_f32_e32 v210, v210, v211
	v_add_f32_e32 v204, v204, v206
	v_add_f32_e32 v208, v208, v210
	v_add_f32_e32 v230, v204, v208
	v_add_f32_e32 v211, v195, v230
	v_cmp_ge_f32_e32 vcc, 0x47800000, v211
	s_cmp_eq_u64 vcc, exec
	s_cbranch_scc0 .Lattn_slow
	v_add_f32_e32 v156, v156, v195
	v_add_f32_e32 v154, v154, v230
	v_cvt_pk_bf16_f32 v119, v118, v119
	v_cvt_pk_bf16_f32 v118, v116, v117
	v_cvt_pk_bf16_f32 v116, v112, v113
	v_cvt_pk_bf16_f32 v117, v114, v115
	v_cvt_pk_bf16_f32 v112, v136, v137
	v_cvt_pk_bf16_f32 v113, v138, v139
	v_cvt_pk_bf16_f32 v114, v140, v141
	v_cvt_pk_bf16_f32 v115, v142, v143
	v_cvt_pk_bf16_f32 v127, v126, v127
	v_cvt_pk_bf16_f32 v126, v124, v125
	v_cvt_pk_bf16_f32 v124, v120, v121
	v_cvt_pk_bf16_f32 v125, v122, v123
	v_cvt_pk_bf16_f32 v120, v128, v129
	v_cvt_pk_bf16_f32 v121, v130, v131
	v_cvt_pk_bf16_f32 v122, v132, v133
	v_cvt_pk_bf16_f32 v123, v134, v135

.LBB0_1007:
	v_add_f32_e32 v155, 0, v155
	v_add_f32_e32 v155, v204, v155
	v_add_f32_e32 v155, v205, v155
	v_add_f32_e32 v155, v206, v155
	v_add_f32_e32 v155, v207, v155
	v_add_f32_e32 v155, v208, v155
	v_add_f32_e32 v155, v230, v155
	v_add_f32_e32 v155, v195, v155
	v_add_f32_e32 v136, v136, v155
	v_add_f32_e32 v136, v137, v136
	v_add_f32_e32 v136, v138, v136
	v_mul_f32_e32 v155, 0xbdd53b94, v203
	v_add_f32_e32 v136, v139, v136
	v_fmamk_f32 v120, v120, 0x3dd53b94, v155
	v_add_f32_e32 v136, v140, v136
	v_exp_f32_e32 v120, v120
	v_fmamk_f32 v121, v121, 0x3dd53b94, v155
	v_add_f32_e32 v136, v141, v136
	v_exp_f32_e32 v121, v121
	v_fmamk_f32 v122, v122, 0x3dd53b94, v155
	v_add_f32_e32 v136, v142, v136
	v_exp_f32_e32 v122, v122
	v_fmamk_f32 v123, v123, 0x3dd53b94, v155
	v_add_f32_e32 v136, v143, v136
	v_exp_f32_e32 v123, v123
	v_fmamk_f32 v124, v124, 0x3dd53b94, v155
	v_add_f32_e32 v156, v156, v136
	v_add_f32_e32 v136, 0, v120
	v_exp_f32_e32 v137, v124
	v_add_f32_e32 v136, v121, v136
	v_add_f32_e32 v136, v122, v136
	v_add_f32_e32 v136, v123, v136
	v_fmamk_f32 v125, v125, 0x3dd53b94, v155
	v_add_f32_e32 v124, v137, v136
	v_exp_f32_e32 v136, v125
	v_fmamk_f32 v125, v126, 0x3dd53b94, v155
	v_exp_f32_e32 v138, v125
	v_fmamk_f32 v125, v127, 0x3dd53b94, v155
	v_exp_f32_e32 v127, v125
	v_fmamk_f32 v125, v128, 0x3dd53b94, v155
	v_exp_f32_e32 v128, v125
	v_fmamk_f32 v125, v129, 0x3dd53b94, v155
	v_add_f32_e32 v124, v136, v124
	v_exp_f32_e32 v129, v125
	v_fmamk_f32 v125, v130, 0x3dd53b94, v155
	v_add_f32_e32 v124, v138, v124
	v_exp_f32_e32 v130, v125
	v_fmamk_f32 v125, v131, 0x3dd53b94, v155
	v_add_f32_e32 v124, v127, v124
	v_exp_f32_e32 v131, v125
	v_fmamk_f32 v125, v132, 0x3dd53b94, v155
	v_add_f32_e32 v124, v128, v124
	v_exp_f32_e32 v132, v125
	v_fmamk_f32 v125, v133, 0x3dd53b94, v155
	v_add_f32_e32 v124, v129, v124
	v_exp_f32_e32 v133, v125
	v_fmamk_f32 v125, v134, 0x3dd53b94, v155
	v_add_f32_e32 v124, v130, v124
	v_exp_f32_e32 v134, v125
	v_fmamk_f32 v125, v135, 0x3dd53b94, v155
	v_add_f32_e32 v124, v131, v124
	v_exp_f32_e32 v135, v125
	v_add_f32_e32 v124, v132, v124
	v_add_f32_e32 v124, v133, v124
	v_add_f32_e32 v124, v134, v124
	v_add_f32_e32 v124, v135, v124
	v_add_f32_e32 v154, v154, v124
	v_cvt_pk_bf16_f32 v124, v120, v121
	v_cvt_pk_bf16_f32 v125, v122, v123
	v_cvt_pk_bf16_f32 v126, v137, v136
	v_cvt_pk_bf16_f32 v127, v138, v127
	v_cvt_pk_bf16_f32 v120, v128, v129
	v_cvt_pk_bf16_f32 v121, v130, v131
	v_cvt_pk_bf16_f32 v122, v132, v133
	v_cvt_pk_bf16_f32 v123, v134, v135
	s_branch .Lattn_pv
.LBB0_1011:
	v_add_u32_e32 v112, s12, v198
	ds_read_b128 v[112:115], v112
	v_add_u32_e32 v120, s12, v199
	ds_read_b128 v[120:123], v120
	v_add_u32_e32 v136, s12, v241
	v_add_u32_e32 v128, s12, v235
	s_waitcnt lgkmcnt(1)
	v_mfma_f32_16x16x32_bf16 v[116:119], v[112:115], v[104:107], 0
	ds_read_b128 v[136:139], v136
	ds_read_b128 v[128:131], v128
	v_mfma_f32_16x16x32_bf16 v[112:115], v[112:115], v[108:111], 0
	s_waitcnt lgkmcnt(2)
	v_mfma_f32_16x16x32_bf16 v[116:119], v[120:123], v[96:99], v[116:119]
	v_mfma_f32_16x16x32_bf16 v[112:115], v[120:123], v[100:103], v[112:115]
	v_add_u32_e32 v120, s12, v200
	ds_read_b128 v[120:123], v120
	s_waitcnt lgkmcnt(0)
	v_mfma_f32_16x16x32_bf16 v[116:119], v[120:123], v[88:91], v[116:119]
	v_mfma_f32_16x16x32_bf16 v[112:115], v[120:123], v[92:95], v[112:115]
	v_add_u32_e32 v120, s12, v201
	ds_read_b128 v[120:123], v120
	s_waitcnt lgkmcnt(0)
	v_mfma_f32_16x16x32_bf16 v[116:119], v[120:123], v[80:83], v[116:119]
	v_mfma_f32_16x16x32_bf16 v[112:115], v[120:123], v[84:87], v[112:115]
	v_add_u32_e32 v120, s12, v225
	ds_read_b128 v[120:123], v120
	s_waitcnt lgkmcnt(0)
	v_mfma_f32_16x16x32_bf16 v[116:119], v[120:123], v[72:75], v[116:119]
	v_mfma_f32_16x16x32_bf16 v[112:115], v[120:123], v[76:79], v[112:115]
	v_add_u32_e32 v120, s12, v226
	ds_read_b128 v[120:123], v120
	s_waitcnt lgkmcnt(0)
	v_mfma_f32_16x16x32_bf16 v[124:127], v[120:123], v[64:67], v[116:119]
	s_nop 2
	v_add_u32_e32 v116, s12, v234
	ds_read_b128 v[116:119], v116
	v_mfma_f32_16x16x32_bf16 v[112:115], v[120:123], v[68:71], v[112:115]
	s_waitcnt lgkmcnt(0)
	v_mfma_f32_16x16x32_bf16 v[120:123], v[116:119], v[104:107], 0
	v_mfma_f32_16x16x32_bf16 v[116:119], v[116:119], v[108:111], 0
	v_mfma_f32_16x16x32_bf16 v[120:123], v[128:131], v[96:99], v[120:123]
	v_mfma_f32_16x16x32_bf16 v[116:119], v[128:131], v[100:103], v[116:119]
	v_add_u32_e32 v128, s12, v236
	ds_read_b128 v[128:131], v128
	s_waitcnt lgkmcnt(0)
	v_mfma_f32_16x16x32_bf16 v[120:123], v[128:131], v[88:91], v[120:123]
	v_mfma_f32_16x16x32_bf16 v[116:119], v[128:131], v[92:95], v[116:119]
	v_add_u32_e32 v128, s12, v237
	ds_read_b128 v[128:131], v128
	s_waitcnt lgkmcnt(0)
	v_mfma_f32_16x16x32_bf16 v[120:123], v[128:131], v[80:83], v[120:123]
	v_mfma_f32_16x16x32_bf16 v[116:119], v[128:131], v[84:87], v[116:119]
	v_add_u32_e32 v128, s12, v238
	ds_read_b128 v[128:131], v128
	s_waitcnt lgkmcnt(0)
	v_mfma_f32_16x16x32_bf16 v[120:123], v[128:131], v[72:75], v[120:123]
	v_mfma_f32_16x16x32_bf16 v[116:119], v[128:131], v[76:79], v[116:119]
	v_add_u32_e32 v128, s12, v239
	ds_read_b128 v[132:135], v128
	s_waitcnt lgkmcnt(0)
	v_mfma_f32_16x16x32_bf16 v[128:131], v[132:135], v[64:67], v[120:123]
	s_nop 2
	v_add_u32_e32 v120, s12, v240
	ds_read_b128 v[120:123], v120
	v_mfma_f32_16x16x32_bf16 v[116:119], v[132:135], v[68:71], v[116:119]
	s_waitcnt lgkmcnt(0)
	v_mfma_f32_16x16x32_bf16 v[132:135], v[120:123], v[104:107], 0
	v_mfma_f32_16x16x32_bf16 v[120:123], v[120:123], v[108:111], 0
	v_mfma_f32_16x16x32_bf16 v[132:135], v[136:139], v[96:99], v[132:135]
	v_mfma_f32_16x16x32_bf16 v[120:123], v[136:139], v[100:103], v[120:123]
	v_add_u32_e32 v136, s12, v242
	ds_read_b128 v[136:139], v136
	s_waitcnt lgkmcnt(0)
	v_mfma_f32_16x16x32_bf16 v[132:135], v[136:139], v[88:91], v[132:135]
	v_mfma_f32_16x16x32_bf16 v[120:123], v[136:139], v[92:95], v[120:123]
	v_add_u32_e32 v136, s12, v243
	ds_read_b128 v[136:139], v136
	s_waitcnt lgkmcnt(0)
	v_mfma_f32_16x16x32_bf16 v[132:135], v[136:139], v[80:83], v[132:135]
	v_mfma_f32_16x16x32_bf16 v[120:123], v[136:139], v[84:87], v[120:123]
	v_add_u32_e32 v136, s12, v244
	ds_read_b128 v[136:139], v136
	s_waitcnt lgkmcnt(0)
	v_mfma_f32_16x16x32_bf16 v[132:135], v[136:139], v[72:75], v[132:135]
	v_mfma_f32_16x16x32_bf16 v[120:123], v[136:139], v[76:79], v[120:123]
	v_add_u32_e32 v136, s12, v245
	ds_read_b128 v[136:139], v136
	s_waitcnt lgkmcnt(0)
	v_mfma_f32_16x16x32_bf16 v[132:135], v[136:139], v[64:67], v[132:135]
	v_mfma_f32_16x16x32_bf16 v[120:123], v[136:139], v[68:71], v[120:123]
	v_add_u32_e32 v136, s12, v246
	ds_read_b128 v[136:139], v136
	s_waitcnt lgkmcnt(0)
	v_mfma_f32_16x16x32_bf16 v[104:107], v[136:139], v[104:107], 0
	v_mfma_f32_16x16x32_bf16 v[108:111], v[136:139], v[108:111], 0
	v_add_u32_e32 v136, s12, v247
	ds_read_b128 v[136:139], v136
	s_waitcnt lgkmcnt(0)
	v_mfma_f32_16x16x32_bf16 v[96:99], v[136:139], v[96:99], v[104:107]
	s_nop 2
	v_add_u32_e32 v104, s12, v248
	ds_read_b128 v[104:107], v104
	s_waitcnt lgkmcnt(0)
	v_mfma_f32_16x16x32_bf16 v[88:91], v[104:107], v[88:91], v[96:99]
	s_nop 2
	v_add_u32_e32 v96, s12, v249
	ds_read_b128 v[96:99], v96
	s_waitcnt lgkmcnt(0)
	v_mfma_f32_16x16x32_bf16 v[80:83], v[96:99], v[80:83], v[88:91]
	s_nop 2
	v_add_u32_e32 v88, s12, v250
	ds_read_b128 v[88:91], v88
	v_mfma_f32_16x16x32_bf16 v[100:103], v[136:139], v[100:103], v[108:111]
	v_mfma_f32_16x16x32_bf16 v[92:95], v[104:107], v[92:95], v[100:103]
	s_waitcnt lgkmcnt(0)
	v_mfma_f32_16x16x32_bf16 v[72:75], v[88:91], v[72:75], v[80:83]
	s_nop 2
	v_add_u32_e32 v80, s12, v251
	ds_read_b128 v[80:83], v80
	v_mfma_f32_16x16x32_bf16 v[84:87], v[96:99], v[84:87], v[92:95]
	v_mfma_f32_16x16x32_bf16 v[76:79], v[88:91], v[76:79], v[84:87]
	s_waitcnt lgkmcnt(0)
	v_mfma_f32_16x16x32_bf16 v[64:67], v[80:83], v[64:67], v[72:75]
	v_mfma_f32_16x16x32_bf16 v[72:75], v[80:83], v[68:71], v[76:79]
	v_max_f32_e32 v68, v125, v125
	v_max_f32_e32 v69, v124, v124
	v_max_f32_e32 v68, v69, v68
	v_max_f32_e32 v69, v127, v127
	v_max_f32_e32 v70, v126, v126
	v_max_f32_e32 v69, v70, v69
	v_max_f32_e32 v70, v131, v131
	v_max_f32_e32 v71, v130, v130
	v_max_f32_e32 v70, v71, v70
	v_max3_f32 v70, v128, v129, v70
	v_max3_f32 v68, v68, v69, v70
	v_max_f32_e32 v69, v135, v135
	v_max_f32_e32 v70, v134, v134
	v_max_f32_e32 v69, v70, v69
	v_max_f32_e32 v70, v67, v67
	v_max_f32_e32 v71, v66, v66
	v_max_f32_e32 v70, v71, v70
	v_max3_f32 v69, v132, v133, v69
	v_max3_f32 v70, v64, v65, v70
	v_max3_f32 v68, v68, v69, v70
	v_sub_f32_e32 v69, v68, v162
	v_cmp_ge_f32_e32 vcc, s89, v69
	s_cmp_eq_u64 vcc, exec
	s_cbranch_scc1 .LBB0_1013
	v_and_b32_e32 v70, 64, v227
	v_xor_b32_e32 v69, 16, v227
	v_add_u32_e32 v70, 64, v70
	v_cmp_lt_i32_e32 vcc, v69, v70
	s_nop 1
	v_cndmask_b32_e32 v69, v227, v69, vcc
	v_lshlrev_b32_e32 v69, 2, v69
	ds_bpermute_b32 v69, v69, v68
	v_max_f32_e32 v68, v68, v68
	s_waitcnt lgkmcnt(0)
	v_max_f32_e32 v69, v69, v69
	v_max_f32_e32 v68, v68, v69
	v_xor_b32_e32 v69, 32, v227
	v_cmp_lt_i32_e32 vcc, v69, v70
	s_nop 1
	v_cndmask_b32_e32 v69, v227, v69, vcc
	v_lshlrev_b32_e32 v69, 2, v69
	ds_bpermute_b32 v69, v69, v68
	s_waitcnt lgkmcnt(0)
	v_max3_f32 v157, v162, v68, v69
	v_sub_f32_e32 v68, v162, v157
	v_mul_f32_e32 v68, 0x3dd53b94, v68
	v_exp_f32_e32 v162, v68
	s_nop 0
	v_pk_mul_f32 v[62:63], v[62:63], v[162:163] op_sel_hi:[1,0]
	v_pk_mul_f32 v[60:61], v[60:61], v[162:163] op_sel_hi:[1,0]
	v_pk_mul_f32 v[54:55], v[54:55], v[162:163] op_sel_hi:[1,0]
	v_pk_mul_f32 v[52:53], v[52:53], v[162:163] op_sel_hi:[1,0]
	v_pk_mul_f32 v[46:47], v[46:47], v[162:163] op_sel_hi:[1,0]
	v_pk_mul_f32 v[44:45], v[44:45], v[162:163] op_sel_hi:[1,0]
	v_pk_mul_f32 v[38:39], v[38:39], v[162:163] op_sel_hi:[1,0]
	v_pk_mul_f32 v[36:37], v[36:37], v[162:163] op_sel_hi:[1,0]
	v_pk_mul_f32 v[26:27], v[26:27], v[162:163] op_sel_hi:[1,0]
	v_pk_mul_f32 v[24:25], v[24:25], v[162:163] op_sel_hi:[1,0]
	v_pk_mul_f32 v[18:19], v[18:19], v[162:163] op_sel_hi:[1,0]
	v_pk_mul_f32 v[16:17], v[16:17], v[162:163] op_sel_hi:[1,0]
	v_pk_mul_f32 v[10:11], v[10:11], v[162:163] op_sel_hi:[1,0]
	v_pk_mul_f32 v[8:9], v[8:9], v[162:163] op_sel_hi:[1,0]
	v_pk_mul_f32 v[2:3], v[2:3], v[162:163] op_sel_hi:[1,0]
	v_pk_mul_f32 v[0:1], v[0:1], v[162:163] op_sel_hi:[1,0]
	v_pk_mul_f32 v[156:157], v[156:157], v[162:163]
